# all weight conversion except w_in_ab moved from phase 0 into idle workgroups of phases 1,5,7,8,11; phase 0 keeps w_in_ab + x
# speedup vs baseline: 1.0301x; 1.0020x over previous
; DI void phase0(CP& p, LAS unsigned char* lds, int wid) {
;     ...
;     const int gw = blockIdx.x * 8 + wid, nw = gridDim.x * 8;
;     for (int it0 = gw; it0 < NCONV + NXROW; it0 += nw) {
;         const int it = it0 < NCONV ? NCONV - 1 - it0 : it0;
.Lconv_entry:
	s_lshl_b32 s2, s6, 3
	v_mbcnt_hi_u32_b32 v5, -1, v254
	s_add_i32 s89, s33, s2
	s_cmp_lg_u32 s98, 0
	s_cbranch_scc1 .Lconv_ext
	s_mul_i32 s89, s33, s7
	s_add_i32 s89, s89, s6
	s_addk_i32 s89, 5136
	s_movk_i32 s101, 0x358f
	s_branch .Lconv_go

; DI void phase0(CP& p, LAS unsigned char* lds, int wid) {
;     ...
;     const int gt = blockIdx.x * NTHR + tid, gs = gridDim.x * NTHR;
;     for (int i = gt; i < 7 * 8192; i += gs) SSQ(1)[i] = 0.f;
.LBB0_225:
	s_cmp_eq_u32 s98, 1
	s_cbranch_scc1 .Lconv_ret_1
	s_cmp_eq_u32 s98, 2
	s_cbranch_scc1 .Lconv_ret_2
	s_cmp_eq_u32 s98, 3
	s_cbranch_scc1 .Lconv_ret_3
	s_cmp_eq_u32 s98, 4
	s_cbranch_scc1 .Lconv_tout_4
	s_cmp_eq_u32 s98, 5
	s_cbranch_scc1 .Lconv_tout_5
	s_cmp_eq_u32 s98, 6
	s_cbranch_scc1 .Lconv_tout_6
	s_load_dwordx2 s[4:5], s[38:39], 0xa8
	s_and_b32 s2, s88, 0xffffffc0
	s_lshl_b32 s3, s6, 9
	s_add_i32 s2, s2, s3
	v_add_u32_e32 v2, s2, v0
	s_mov_b32 s2, 0xe000
	s_waitcnt lgkmcnt(0)
	s_lshl_b32 s10, s7, 9
	v_cmp_gt_i32_e32 vcc, s2, v2
	s_and_saveexec_b64 s[8:9], vcc
	s_cbranch_execz .LBB0_233
	v_cvt_f32_u32_e32 v1, s10
	v_add_u32_e32 v3, s10, v2
	v_mov_b32_e32 v4, s10
	v_cmp_gt_i32_e32 vcc, s2, v3
	v_rcp_iflag_f32_e32 v1, v1
	s_sub_i32 s11, 0, s10
	v_max_i32_e32 v5, 0xe000, v3
	v_addc_co_u32_e64 v4, s[2:3], v2, v4, vcc
	v_mul_f32_e32 v1, 0x4f7ffffe, v1
	v_cvt_u32_f32_e32 v1, v1
	v_sub_u32_e32 v4, v5, v4
	s_mov_b64 s[12:13], -1
	v_mul_lo_u32 v5, s11, v1
	v_mul_hi_u32 v5, v1, v5
	v_add_u32_e32 v1, v1, v5
	v_mul_hi_u32 v1, v4, v1
	v_mul_lo_u32 v5, v1, s10
	v_sub_u32_e32 v4, v4, v5
	v_add_u32_e32 v6, 1, v1
	v_cmp_le_u32_e64 s[2:3], s10, v4
	v_subrev_u32_e32 v5, s10, v4
	s_nop 0
	v_cndmask_b32_e64 v1, v1, v6, s[2:3]
	v_cndmask_b32_e64 v4, v4, v5, s[2:3]
	v_add_u32_e32 v5, 1, v1
	v_cmp_le_u32_e64 s[2:3], s10, v4
	v_mov_b32_e32 v4, v2
	s_nop 0
	v_cndmask_b32_e64 v1, v1, v5, s[2:3]
	v_addc_co_u32_e32 v1, vcc, 1, v1, vcc
	v_cmp_lt_u32_e32 vcc, 1, v1
	s_and_saveexec_b64 s[2:3], vcc
	s_cbranch_execz .LBB0_230
	s_add_u32 s12, s4, 0xcd08000
	s_addc_u32 s13, s5, 0
	v_and_b32_e32 v6, -2, v1
	s_lshl_b32 s11, s7, 10
	s_mov_b32 s16, s11
	s_mov_b64 s[14:15], 0
	v_mov_b32_e32 v7, 0
	v_mov_b32_e32 v8, v6
	v_mov_b64_e32 v[4:5], v[2:3]

; DI void phase0(CP& p, LAS unsigned char* lds, int wid) {
;     ...
;     const int gw = blockIdx.x * 8 + wid, nw = gridDim.x * 8;
;     for (int it0 = gw; it0 < NCONV + NXROW; it0 += nw) {
.LBB0_398:
	s_and_b64 vcc, exec, s[8:9]
	s_cbranch_vccz .Lconv_skip_0
	s_cmpk_eq_i32 s7, 0x100
	s_cbranch_scc0 .Lconv_skip_0
	s_and_b32 s12, s6, 31
	s_lshl_b32 s12, s12, 3
	s_lshr_b32 s13, s6, 5
	s_or_b32 s12, s12, s13
	s_cmpk_lt_u32 s12, 128
	s_cbranch_scc1 .Lconv_skip_0
	s_and_b32 s12, s6, 31
	s_lshl_b32 s12, s12, 3
	s_lshr_b32 s13, s6, 5
	s_or_b32 s12, s12, s13
	s_addk_i32 s12, -128
	s_lshl_b32 s12, s12, 3
	s_add_i32 s12, s12, s33
	s_add_i32 s99, s12, 3472
	s_movk_i32 s101, 5135
	s_movk_i32 s100, 1024
	s_mov_b32 s98, 1
	s_branch .Lconv_entry
.Lconv_ret_1:
	s_and_b32 s12, s6, 31
	s_lshl_b32 s12, s12, 3
	s_lshr_b32 s13, s6, 5
	s_or_b32 s12, s12, s13
	s_addk_i32 s12, -128
	s_lshl_b32 s12, s12, 3
	s_add_i32 s12, s12, s33
	s_sub_i32 s12, 1023, s12
	s_add_i32 s99, s12, 2752
	s_movk_i32 s101, 2767
	s_movk_i32 s100, 16384
	s_mov_b32 s98, 2
	s_branch .Lconv_entry
.Lconv_ret_2:
	s_mov_b32 s98, 0
	s_cmp_lt_i32 s34, 2
	s_cselect_b64 s[8:9], -1, 0
	s_cmp_gt_i32 s35, 1
	s_cselect_b64 s[10:11], -1, 0
	s_and_b64 s[8:9], s[8:9], s[10:11]

; DI void phase0(CP& p, LAS unsigned char* lds, int wid) {
;     ...
;     const int gw = blockIdx.x * 8 + wid, nw = gridDim.x * 8;
;     for (int it0 = gw; it0 < NCONV + NXROW; it0 += nw) {
.LBB0_710:
	s_and_b64 vcc, exec, s[4:5]
	s_cbranch_vccz .Lconv_skip_1
	s_cmpk_eq_i32 s7, 0x100
	s_cbranch_scc0 .Lconv_skip_1
	s_and_b32 s12, s6, 31
	s_lshl_b32 s12, s12, 3
	s_lshr_b32 s13, s6, 5
	s_or_b32 s12, s12, s13
	s_cmpk_lt_u32 s12, 128
	s_cbranch_scc1 .Lconv_skip_1
	s_and_b32 s12, s6, 31
	s_lshl_b32 s12, s12, 3
	s_lshr_b32 s13, s6, 5
	s_or_b32 s12, s12, s13
	s_addk_i32 s12, -128
	s_lshl_b32 s12, s12, 3
	s_add_i32 s12, s12, s33
	s_add_i32 s99, s12, 2368
	s_movk_i32 s101, 3471
	s_movk_i32 s100, 1024
	s_mov_b32 s98, 3
	s_branch .Lconv_entry
.Lconv_ret_3:
	s_mov_b32 s98, 0
	s_cmp_lt_i32 s34, 6
	s_cselect_b64 s[4:5], -1, 0
	s_cmp_gt_i32 s35, 5
	s_cselect_b64 s[10:11], -1, 0
	s_and_b64 s[4:5], s[4:5], s[10:11]

; #define LAS __attribute__((address_space(3)))
; DI int lane_id() { int l = __builtin_amdgcn_mbcnt_hi(-1, __builtin_amdgcn_mbcnt_lo(-1, 0)); asm volatile("" : "+v"(l)); return l; }
; DI unsigned xb_ld(unsigned* q) { return __hip_atomic_load(q, __ATOMIC_RELAXED, __HIP_MEMORY_SCOPE_AGENT); }
; DI unsigned xb_add(unsigned* q, unsigned v) { return __hip_atomic_fetch_add(q, v, __ATOMIC_RELAXED, __HIP_MEMORY_SCOPE_AGENT); }
; DI unsigned xb_xcc_id() { return (unsigned)__builtin_amdgcn_s_getreg((3 << 11) | 20) & 0xFu; }
; #define XB_SPIN(cond, bar) do { unsigned _sp = 0; while (cond) { __builtin_amdgcn_s_sleep(1); \
;     if ((++_sp & 255u) == 0u) { if (xb_ld(&(bar)[XB_TMO])) break; if (_sp > XB_SPIN_CAP) { atomicAdd(&(bar)[XB_TMO], 1u); break; } } } } while (0)
; DI void grid_bar(unsigned* bar, volatile LAS unsigned* st, int wid) {
;     asm volatile("s_waitcnt vmcnt(0)" ::: "memory");
;     __syncthreads();
;     if (wid == 0) {
;         if (lane_id() == 0) {
;             __builtin_amdgcn_s_waitcnt(0);
;             const unsigned x = xb_xcc_id();
;             unsigned nloc = st[0], nx = st[1];
;             if (nloc == 0u) { xcd_barrier_complete(bar, x, nloc, nx); st[0] = nloc; st[1] = nx; }
;             const unsigned old = xb_add(&bar[XB_XSUB(x)], 1u);
;             const unsigned gen = old / nloc;
;             if (old + 1u == (gen + 1u) * nloc) {
;                 __builtin_amdgcn_fence(__ATOMIC_RELEASE, "agent");
;                 asm volatile("s_waitcnt vmcnt(0)" ::: "memory");
;                 const unsigned og = xb_add(&bar[XB_TOP], 1u);
;                 const unsigned tg = og / nx;
;                 if (og + 1u == (tg + 1u) * nx) xb_add(&bar[XB_TOPGEN], 1u);
;                 else XB_SPIN(xb_ld(&bar[XB_TOPGEN]) == tg, bar);
;                 __builtin_amdgcn_fence(__ATOMIC_ACQUIRE, "agent");
;                 xb_add(&bar[XB_XGEN(x)], 1u);
;                 asm volatile("s_waitcnt vmcnt(0)" ::: "memory");
;             } else {
;                 XB_SPIN(xb_ld(&bar[XB_XGEN(x)]) == gen, bar);
.Lconv_tout_6:
	s_branch .Lconv_ret_6
.Lconv_tramp_skip:
	s_cmp_gt_i32 s35, 6
	s_cselect_b64 s[2:3], -1, 0
	s_and_b64 s[4:5], s[4:5], s[2:3]
	s_andn2_b64 vcc, exec, s[4:5]
	s_cbranch_vccnz .LBB0_766
	s_mov_b64 s[8:9], s[0:1]
	s_waitcnt vmcnt(0)
	s_cmp_gt_u32 s88, 63
	s_waitcnt vmcnt(0) lgkmcnt(0)
	s_barrier
	s_cbranch_scc1 .LBB0_765
	v_mbcnt_hi_u32_b32 v0, -1, v254
	s_nop 0
	v_cmp_eq_u32_e32 vcc, 0, v0
	s_and_saveexec_b64 s[4:5], vcc
	s_cbranch_execz .LBB0_764
	s_add_i32 s11, 0, 0x20000
	v_mov_b32_e32 v0, s11
	s_load_dwordx2 s[8:9], s[8:9], 0xa8
	s_waitcnt vmcnt(0) expcnt(0) lgkmcnt(0)
	s_getreg_b32 s10, hwreg(HW_REG_XCC_ID, 0, 4)
	ds_read_b32 v2, v0
	s_add_i32 s11, 0, 0x20004
	v_mov_b32_e32 v0, s11
	ds_read_b32 v0, v0
	s_and_b32 s54, s10, 15
	s_waitcnt lgkmcnt(1)
	v_cmp_ne_u32_e32 vcc, 0, v2
	s_cbranch_vccnz .LBB0_728
	s_add_u32 s10, s8, 0xcd80200
	s_addc_u32 s11, s9, 0
	s_add_u32 s12, s8, 0xcd80400
	s_addc_u32 s13, s9, 0
	s_add_u32 s14, s8, 0xcd80500
	s_addc_u32 s15, s9, 0
	s_add_u32 s16, s8, 0xcd80600
	s_addc_u32 s17, s9, 0
	s_add_u32 s18, s8, 0xcd80700
	s_addc_u32 s19, s9, 0
	s_add_u32 s20, s8, 0xcd80800
	s_addc_u32 s21, s9, 0
	s_add_u32 s22, s8, 0xcd80900
	s_addc_u32 s23, s9, 0
	s_add_u32 s24, s8, 0xcd80a00
	s_addc_u32 s25, s9, 0
	s_add_u32 s26, s8, 0xcd80b00
	s_addc_u32 s27, s9, 0
	s_add_u32 s28, s8, 0xcd80c00
	s_addc_u32 s29, s9, 0
	s_add_u32 s30, s8, 0xcd80d00
	s_addc_u32 s31, s9, 0
	s_add_u32 s36, s8, 0xcd80e00
	s_addc_u32 s37, s9, 0
	s_add_u32 s38, s8, 0xcd80f00
	s_addc_u32 s39, s9, 0
	s_add_u32 s40, s8, 0xcd81000
	s_addc_u32 s41, s9, 0
	s_add_u32 s42, s8, 0xcd81100
	s_addc_u32 s43, s9, 0
	s_add_u32 s44, s8, 0xcd81200
	s_addc_u32 s45, s9, 0
	s_add_u32 s46, s8, 0xcd81300
	s_addc_u32 s47, s9, 0
	s_mov_b32 s55, 1
	v_mov_b32_e32 v16, 0
	s_branch .LBB0_716

; DI void phase0(CP& p, LAS unsigned char* lds, int wid) {
;     ...
;     const int gw = blockIdx.x * 8 + wid, nw = gridDim.x * 8;
;     for (int it0 = gw; it0 < NCONV + NXROW; it0 += nw) {
.LBB0_898:
	s_and_b64 vcc, exec, s[8:9]
	s_cbranch_vccz .Lconv_skip_2
	s_cmpk_eq_i32 s7, 0x100
	s_cbranch_scc0 .Lconv_skip_2
	s_and_b32 s12, s6, 31
	s_lshl_b32 s12, s12, 3
	s_lshr_b32 s13, s6, 5
	s_or_b32 s12, s12, s13
	s_cmpk_lt_u32 s12, 160
	s_cbranch_scc1 .Lconv_skip_2
	s_and_b32 s12, s6, 31
	s_lshl_b32 s12, s12, 3
	s_lshr_b32 s13, s6, 5
	s_or_b32 s12, s12, s13
	s_addk_i32 s12, -160
	s_lshl_b32 s12, s12, 3
	s_add_i32 s12, s12, s33
	s_add_i32 s99, s12, 832
	s_movk_i32 s101, 2367
	s_movk_i32 s100, 768
	s_mov_b32 s98, 4
	s_branch .Lconv_tin
.Lconv_ret_4:
	s_mov_b32 s98, 0
	s_cmp_lt_i32 s34, 8
	s_cselect_b64 s[8:9], -1, 0
	s_cmp_gt_i32 s35, 7
	s_cselect_b64 s[10:11], -1, 0
	s_and_b64 s[8:9], s[8:9], s[10:11]

; DI void phase0(CP& p, LAS unsigned char* lds, int wid) {
;     ...
;     const int gw = blockIdx.x * 8 + wid, nw = gridDim.x * 8;
;     for (int it0 = gw; it0 < NCONV + NXROW; it0 += nw) {
.LBB0_1017:
	s_and_b64 vcc, exec, s[2:3]
	s_cbranch_vccz .Lconv_skip_3
	s_cmpk_eq_i32 s7, 0x100
	s_cbranch_scc0 .Lconv_skip_3
	s_and_b32 s12, s6, 31
	s_lshl_b32 s12, s12, 3
	s_lshr_b32 s13, s6, 5
	s_or_b32 s12, s12, s13
	s_cmpk_lt_u32 s12, 128
	s_cbranch_scc1 .Lconv_skip_3
	s_and_b32 s12, s6, 31
	s_lshl_b32 s12, s12, 3
	s_lshr_b32 s13, s6, 5
	s_or_b32 s12, s12, s13
	s_addk_i32 s12, -128
	s_lshl_b32 s12, s12, 3
	s_add_i32 s12, s12, s33
	s_add_i32 s99, s12, 704
	s_movk_i32 s101, 831
	s_movk_i32 s100, 16384
	s_mov_b32 s98, 5
	s_branch .Lconv_tin
.Lconv_ret_5:
	s_mov_b32 s98, 0
	s_cmp_lt_i32 s34, 9
	s_cselect_b64 s[2:3], -1, 0
	s_cmp_gt_i32 s35, 8
	s_cselect_b64 s[10:11], -1, 0
	s_and_b64 s[2:3], s[2:3], s[10:11]

; DI void phase0(CP& p, LAS unsigned char* lds, int wid) {
;     ...
;     const int gw = blockIdx.x * 8 + wid, nw = gridDim.x * 8;
;     for (int it0 = gw; it0 < NCONV + NXROW; it0 += nw) {
.LBB0_1265:
	s_and_b64 vcc, exec, s[4:5]
	s_cbranch_vccz .Lconv_skip_4
	s_cmpk_eq_i32 s7, 0x100
	s_cbranch_scc0 .Lconv_skip_4
	s_and_b32 s12, s6, 31
	s_lshl_b32 s12, s12, 3
	s_lshr_b32 s13, s6, 5
	s_or_b32 s12, s12, s13
	s_cmpk_lt_u32 s12, 128
	s_cbranch_scc1 .Lconv_skip_4
	s_and_b32 s12, s6, 31
	s_lshl_b32 s12, s12, 3
	s_lshr_b32 s13, s6, 5
	s_or_b32 s12, s12, s13
	s_addk_i32 s12, -128
	s_lshl_b32 s12, s12, 3
	s_add_i32 s12, s12, s33
	s_add_i32 s99, s12, 0
	s_movk_i32 s101, 703
	s_movk_i32 s100, 16384
	s_mov_b32 s98, 6
	s_branch .Lconv_tin
.Lconv_ret_6:
	s_mov_b32 s98, 0
	s_cmp_lt_i32 s34, 12
	s_cselect_b64 s[4:5], -1, 0
	s_cmp_gt_i32 s35, 11
	s_cselect_b64 s[10:11], -1, 0
	s_and_b64 s[4:5], s[4:5], s[10:11]
